# la_unit second part restructured: weights of 4 column blocks preloaded, rows outer with 4 interleaved chains (same per-output arithmetic order); on top of the fragment split
# speedup vs baseline: 1.0214x; 1.0057x over previous
; #define LAS __attribute__((address_space(3)))
; DI float log_sigmoid_f(float x) { return fminf(x, 0.f) - 0.6931471805599453f * __builtin_amdgcn_logf(1.0f + fexp(-__builtin_fabsf(x))); }
; DI void la_unit(const bf16* __restrict__ XB, const bf16* __restrict__ W16, const float* SS, const float* __restrict__ wa2, const float* __restrict__ ba, float* __restrict__ LA, LAS float* scr, int row0, int lane) {
;     ...
;     for (int nb = 0; nb < 8; ++nb) {
;         float w[16];
; #pragma unroll
;         for (int rk = 0; rk < 16; ++rk) w[rk] = wa2[rk * 512 + 64 * nb + lane];
;         const float bb = ba[64 * nb + lane];
; #pragma unroll 4
;         for (int row = 0; row < 16; ++row) {
;             const f32x4 a0 = *(const LAS f32x4*)(scr + row * 16), a1 = *(const LAS f32x4*)(scr + row * 16 + 4), a2 = *(const LAS f32x4*)(scr + row * 16 + 8), a3 = *(const LAS f32x4*)(scr + row * 16 + 12);
;             float pre = bb;
; #pragma unroll
;             for (int q = 0; q < 4; ++q) pre += a0[q] * w[q] + a1[q] * w[4 + q] + a2[q] * w[8 + q] + a3[q] * w[12 + q];
;             LA[(size_t)(row0 + row) * 512 + 64 * nb + lane] = log_sigmoid_f(pre) * 0.0625f;
;         }
;     }
.LBB0_244:
	s_add_i32 s9, s8, 0
	v_lshl_or_b32 v6, s9, 6, v48
	v_lshlrev_b32_e32 v6, 2, v6
	s_add_i32 s9, s8, 1
	v_lshl_or_b32 v7, s9, 6, v48
	v_lshlrev_b32_e32 v7, 2, v7
	s_add_i32 s9, s8, 2
	v_lshl_or_b32 v8, s9, 6, v48
	v_lshlrev_b32_e32 v8, 2, v8
	s_add_i32 s9, s8, 3
	v_lshl_or_b32 v9, s9, 6, v48
	v_lshlrev_b32_e32 v9, 2, v9
	s_mov_b64 s[14:15], s[4:5]
	s_waitcnt vmcnt(0)
	global_load_dword v60, v6, s[14:15]
	global_load_dword v61, v6, s[14:15] offset:2048
	global_load_dword v78, v7, s[14:15]
	global_load_dword v79, v7, s[14:15] offset:2048
	global_load_dword v96, v8, s[14:15]
	global_load_dword v97, v8, s[14:15] offset:2048
	global_load_dword v114, v9, s[14:15]
	global_load_dword v115, v9, s[14:15] offset:2048
	s_add_u32 s14, s14, 0x1000
	s_addc_u32 s15, s15, 0
	global_load_dword v62, v6, s[14:15]
	global_load_dword v63, v6, s[14:15] offset:2048
	global_load_dword v80, v7, s[14:15]
	global_load_dword v81, v7, s[14:15] offset:2048
	global_load_dword v98, v8, s[14:15]
	global_load_dword v99, v8, s[14:15] offset:2048
	global_load_dword v116, v9, s[14:15]
	global_load_dword v117, v9, s[14:15] offset:2048
	s_add_u32 s14, s14, 0x1000
	s_addc_u32 s15, s15, 0
	global_load_dword v64, v6, s[14:15]
	global_load_dword v65, v6, s[14:15] offset:2048
	global_load_dword v82, v7, s[14:15]
	global_load_dword v83, v7, s[14:15] offset:2048
	global_load_dword v100, v8, s[14:15]
	global_load_dword v101, v8, s[14:15] offset:2048
	global_load_dword v118, v9, s[14:15]
	global_load_dword v119, v9, s[14:15] offset:2048
	s_add_u32 s14, s14, 0x1000
	s_addc_u32 s15, s15, 0
	global_load_dword v66, v6, s[14:15]
	global_load_dword v67, v6, s[14:15] offset:2048
	global_load_dword v84, v7, s[14:15]
	global_load_dword v85, v7, s[14:15] offset:2048
	global_load_dword v102, v8, s[14:15]
	global_load_dword v103, v8, s[14:15] offset:2048
	global_load_dword v120, v9, s[14:15]
	global_load_dword v121, v9, s[14:15] offset:2048
	s_add_u32 s14, s14, 0x1000
	s_addc_u32 s15, s15, 0
	global_load_dword v68, v6, s[14:15]
	global_load_dword v69, v6, s[14:15] offset:2048
	global_load_dword v86, v7, s[14:15]
	global_load_dword v87, v7, s[14:15] offset:2048
	global_load_dword v104, v8, s[14:15]
	global_load_dword v105, v8, s[14:15] offset:2048
	global_load_dword v122, v9, s[14:15]
	global_load_dword v123, v9, s[14:15] offset:2048
	s_add_u32 s14, s14, 0x1000
	s_addc_u32 s15, s15, 0
	s_waitcnt vmcnt(40)
	global_load_dword v70, v6, s[14:15]
	global_load_dword v71, v6, s[14:15] offset:2048
	global_load_dword v88, v7, s[14:15]
	global_load_dword v89, v7, s[14:15] offset:2048
	global_load_dword v106, v8, s[14:15]
	global_load_dword v107, v8, s[14:15] offset:2048
	global_load_dword v124, v9, s[14:15]
	global_load_dword v125, v9, s[14:15] offset:2048
	s_add_u32 s14, s14, 0x1000
	s_addc_u32 s15, s15, 0
	s_waitcnt vmcnt(40)
	global_load_dword v72, v6, s[14:15]
	global_load_dword v73, v6, s[14:15] offset:2048
	global_load_dword v90, v7, s[14:15]
	global_load_dword v91, v7, s[14:15] offset:2048
	global_load_dword v108, v8, s[14:15]
	global_load_dword v109, v8, s[14:15] offset:2048
	global_load_dword v126, v9, s[14:15]
	global_load_dword v127, v9, s[14:15] offset:2048
	s_add_u32 s14, s14, 0x1000
	s_addc_u32 s15, s15, 0
	s_waitcnt vmcnt(40)
	global_load_dword v74, v6, s[14:15]
	global_load_dword v75, v6, s[14:15] offset:2048
	global_load_dword v92, v7, s[14:15]
	global_load_dword v93, v7, s[14:15] offset:2048
	global_load_dword v110, v8, s[14:15]
	global_load_dword v111, v8, s[14:15] offset:2048
	global_load_dword v128, v9, s[14:15]
	global_load_dword v129, v9, s[14:15] offset:2048
	s_waitcnt vmcnt(40)
	global_load_dword v76, v6, s[6:7]
	global_load_dword v94, v7, s[6:7]
	global_load_dword v112, v8, s[6:7]
	global_load_dword v130, v9, s[6:7]
	s_mov_b32 s9, s3
	s_mov_b64 s[10:11], 0x800
	s_mov_b64 s[14:15], 0x2e500000
	v_lshl_add_u64 v[10:11], v[4:5], 0, s[14:15]
	v_mov_b32_e32 v12, s9
	ds_read_b128 v[22:25], v12 offset:0
	ds_read_b128 v[26:29], v12 offset:16
	ds_read_b128 v[30:33], v12 offset:32
	ds_read_b128 v[34:37], v12 offset:48
	s_mov_b32 s12, 0
	s_waitcnt vmcnt(0)
.Lla_rows:
	s_waitcnt vmcnt(48)
	s_addk_i32 s9, 0x40
	v_mov_b32_e32 v12, s9
	s_waitcnt lgkmcnt(0)
	ds_read_b128 v[170:173], v12 offset:0
	ds_read_b128 v[174:177], v12 offset:16
	ds_read_b128 v[178:181], v12 offset:32
	ds_read_b128 v[182:185], v12 offset:48
	v_pk_mul_f32 v[132:133], v[64:65], v[26:27]
	v_pk_mul_f32 v[138:139], v[82:83], v[26:27]
	v_pk_mul_f32 v[144:145], v[100:101], v[26:27]
	v_pk_mul_f32 v[150:151], v[118:119], v[26:27]
	v_pk_fma_f32 v[132:133], v[60:61], v[22:23], v[132:133]
	v_pk_fma_f32 v[138:139], v[78:79], v[22:23], v[138:139]
	v_pk_fma_f32 v[144:145], v[96:97], v[22:23], v[144:145]
	v_pk_fma_f32 v[150:151], v[114:115], v[22:23], v[150:151]
	v_pk_fma_f32 v[132:133], v[68:69], v[30:31], v[132:133]
	v_pk_fma_f32 v[138:139], v[86:87], v[30:31], v[138:139]
	v_pk_fma_f32 v[144:145], v[104:105], v[30:31], v[144:145]
	v_pk_fma_f32 v[150:151], v[122:123], v[30:31], v[150:151]
	v_pk_fma_f32 v[132:133], v[72:73], v[34:35], v[132:133]
	v_pk_fma_f32 v[138:139], v[90:91], v[34:35], v[138:139]
	v_pk_fma_f32 v[144:145], v[108:109], v[34:35], v[144:145]
	v_pk_fma_f32 v[150:151], v[126:127], v[34:35], v[150:151]
	v_add_f32_e32 v132, v76, v132
	v_add_f32_e32 v138, v94, v138
	v_add_f32_e32 v144, v112, v144
	v_add_f32_e32 v150, v130, v150
	v_add_f32_e32 v136, v133, v132
	v_add_f32_e32 v142, v139, v138
	v_add_f32_e32 v148, v145, v144
	v_add_f32_e32 v154, v151, v150
	v_pk_mul_f32 v[134:135], v[66:67], v[28:29]
	v_pk_mul_f32 v[140:141], v[84:85], v[28:29]
	v_pk_mul_f32 v[146:147], v[102:103], v[28:29]
	v_pk_mul_f32 v[152:153], v[120:121], v[28:29]
; #define LAS __attribute__((address_space(3)))
; DI float log_sigmoid_f(float x) { return fminf(x, 0.f) - 0.6931471805599453f * __builtin_amdgcn_logf(1.0f + fexp(-__builtin_fabsf(x))); }
; DI void la_unit(const bf16* __restrict__ XB, const bf16* __restrict__ W16, const float* SS, const float* __restrict__ wa2, const float* __restrict__ ba, float* __restrict__ LA, LAS float* scr, int row0, int lane) {
;     ...
;         for (int row = 0; row < 16; ++row) {
;             const f32x4 a0 = *(const LAS f32x4*)(scr + row * 16), a1 = *(const LAS f32x4*)(scr + row * 16 + 4), a2 = *(const LAS f32x4*)(scr + row * 16 + 8), a3 = *(const LAS f32x4*)(scr + row * 16 + 12);
;             float pre = bb;
; #pragma unroll
;             for (int q = 0; q < 4; ++q) pre += a0[q] * w[q] + a1[q] * w[4 + q] + a2[q] * w[8 + q] + a3[q] * w[12 + q];
;             LA[(size_t)(row0 + row) * 512 + 64 * nb + lane] = log_sigmoid_f(pre) * 0.0625f;
;         }
;     }
	v_pk_fma_f32 v[134:135], v[62:63], v[24:25], v[134:135]
	v_pk_fma_f32 v[140:141], v[80:81], v[24:25], v[140:141]
	v_pk_fma_f32 v[146:147], v[98:99], v[24:25], v[146:147]
	v_pk_fma_f32 v[152:153], v[116:117], v[24:25], v[152:153]
	v_pk_fma_f32 v[134:135], v[70:71], v[32:33], v[134:135]
	v_pk_fma_f32 v[140:141], v[88:89], v[32:33], v[140:141]
	v_pk_fma_f32 v[146:147], v[106:107], v[32:33], v[146:147]
	v_pk_fma_f32 v[152:153], v[124:125], v[32:33], v[152:153]
	v_pk_fma_f32 v[134:135], v[74:75], v[36:37], v[134:135]
	v_pk_fma_f32 v[140:141], v[92:93], v[36:37], v[140:141]
	v_pk_fma_f32 v[146:147], v[110:111], v[36:37], v[146:147]
	v_pk_fma_f32 v[152:153], v[128:129], v[36:37], v[152:153]
	v_add_f32_e32 v134, v134, v136
	v_add_f32_e32 v140, v140, v142
	v_add_f32_e32 v146, v146, v148
	v_add_f32_e32 v152, v152, v154
	v_add_f32_e32 v134, v135, v134
	v_add_f32_e32 v140, v141, v140
	v_add_f32_e32 v146, v147, v146
	v_add_f32_e32 v152, v153, v152
	v_min_f32_e32 v135, 0, v134
	v_min_f32_e32 v141, 0, v140
	v_min_f32_e32 v147, 0, v146
	v_min_f32_e32 v153, 0, v152
	v_mul_f32_e64 v134, |v134|, s90
	v_mul_f32_e64 v140, |v140|, s90
	v_mul_f32_e64 v146, |v146|, s90
	v_mul_f32_e64 v152, |v152|, s90
	v_exp_f32_e32 v134, v134
	v_exp_f32_e32 v140, v140
	v_exp_f32_e32 v146, v146
	v_exp_f32_e32 v152, v152
	v_add_f32_e32 v134, 1.0, v134
	v_add_f32_e32 v140, 1.0, v140
	v_add_f32_e32 v146, 1.0, v146
	v_add_f32_e32 v152, 1.0, v152
	v_log_f32_e32 v134, v134
	v_log_f32_e32 v140, v140
	v_log_f32_e32 v146, v146
	v_log_f32_e32 v152, v152
	v_fmac_f32_e32 v135, 0xbf317218, v134
	v_fmac_f32_e32 v141, 0xbf317218, v140
	v_fmac_f32_e32 v147, 0xbf317218, v146
	v_fmac_f32_e32 v153, 0xbf317218, v152
	v_mul_f32_e32 v137, 0x3d800000, v135
	v_mul_f32_e32 v143, 0x3d800000, v141
	v_mul_f32_e32 v149, 0x3d800000, v147
	v_mul_f32_e32 v155, 0x3d800000, v153
	global_store_dword v[10:11], v137, off
	global_store_dword v[10:11], v143, off offset:256
	global_store_dword v[10:11], v149, off offset:512
	global_store_dword v[10:11], v155, off offset:768
	v_lshl_add_u64 v[10:11], v[10:11], 0, s[10:11]
	s_waitcnt vmcnt(48)
	s_addk_i32 s9, 0x40
	v_mov_b32_e32 v12, s9
	s_waitcnt lgkmcnt(0)
	ds_read_b128 v[22:25], v12 offset:0
	ds_read_b128 v[26:29], v12 offset:16
	ds_read_b128 v[30:33], v12 offset:32
	ds_read_b128 v[34:37], v12 offset:48
	v_pk_mul_f32 v[132:133], v[64:65], v[174:175]
	v_pk_mul_f32 v[138:139], v[82:83], v[174:175]
	v_pk_mul_f32 v[144:145], v[100:101], v[174:175]
	v_pk_mul_f32 v[150:151], v[118:119], v[174:175]
	v_pk_fma_f32 v[132:133], v[60:61], v[170:171], v[132:133]
	v_pk_fma_f32 v[138:139], v[78:79], v[170:171], v[138:139]
	v_pk_fma_f32 v[144:145], v[96:97], v[170:171], v[144:145]
	v_pk_fma_f32 v[150:151], v[114:115], v[170:171], v[150:151]
	v_pk_fma_f32 v[132:133], v[68:69], v[178:179], v[132:133]
	v_pk_fma_f32 v[138:139], v[86:87], v[178:179], v[138:139]
	v_pk_fma_f32 v[144:145], v[104:105], v[178:179], v[144:145]
	v_pk_fma_f32 v[150:151], v[122:123], v[178:179], v[150:151]
	v_pk_fma_f32 v[132:133], v[72:73], v[182:183], v[132:133]
	v_pk_fma_f32 v[138:139], v[90:91], v[182:183], v[138:139]
	v_pk_fma_f32 v[144:145], v[108:109], v[182:183], v[144:145]
	v_pk_fma_f32 v[150:151], v[126:127], v[182:183], v[150:151]
	v_add_f32_e32 v132, v76, v132
	v_add_f32_e32 v138, v94, v138
	v_add_f32_e32 v144, v112, v144
	v_add_f32_e32 v150, v130, v150
	v_add_f32_e32 v136, v133, v132
	v_add_f32_e32 v142, v139, v138
	v_add_f32_e32 v148, v145, v144
	v_add_f32_e32 v154, v151, v150
	v_pk_mul_f32 v[134:135], v[66:67], v[176:177]
	v_pk_mul_f32 v[140:141], v[84:85], v[176:177]
	v_pk_mul_f32 v[146:147], v[102:103], v[176:177]
	v_pk_mul_f32 v[152:153], v[120:121], v[176:177]
	v_pk_fma_f32 v[134:135], v[62:63], v[172:173], v[134:135]
	v_pk_fma_f32 v[140:141], v[80:81], v[172:173], v[140:141]
	v_pk_fma_f32 v[146:147], v[98:99], v[172:173], v[146:147]
	v_pk_fma_f32 v[152:153], v[116:117], v[172:173], v[152:153]
	v_pk_fma_f32 v[134:135], v[70:71], v[180:181], v[134:135]
	v_pk_fma_f32 v[140:141], v[88:89], v[180:181], v[140:141]
	v_pk_fma_f32 v[146:147], v[106:107], v[180:181], v[146:147]
	v_pk_fma_f32 v[152:153], v[124:125], v[180:181], v[152:153]
	v_pk_fma_f32 v[134:135], v[74:75], v[184:185], v[134:135]
	v_pk_fma_f32 v[140:141], v[92:93], v[184:185], v[140:141]
	v_pk_fma_f32 v[146:147], v[110:111], v[184:185], v[146:147]
	v_pk_fma_f32 v[152:153], v[128:129], v[184:185], v[152:153]
	v_add_f32_e32 v134, v134, v136
	v_add_f32_e32 v140, v140, v142
	v_add_f32_e32 v146, v146, v148
	v_add_f32_e32 v152, v152, v154
	v_add_f32_e32 v134, v135, v134
	v_add_f32_e32 v140, v141, v140
	v_add_f32_e32 v146, v147, v146
	v_add_f32_e32 v152, v153, v152
	v_min_f32_e32 v135, 0, v134
	v_min_f32_e32 v141, 0, v140
	v_min_f32_e32 v147, 0, v146
	v_min_f32_e32 v153, 0, v152
	v_mul_f32_e64 v134, |v134|, s90
	v_mul_f32_e64 v140, |v140|, s90
	v_mul_f32_e64 v146, |v146|, s90
	v_mul_f32_e64 v152, |v152|, s90
	v_exp_f32_e32 v134, v134
	v_exp_f32_e32 v140, v140
	v_exp_f32_e32 v146, v146
	v_exp_f32_e32 v152, v152
	v_add_f32_e32 v134, 1.0, v134
	v_add_f32_e32 v140, 1.0, v140
	v_add_f32_e32 v146, 1.0, v146
	v_add_f32_e32 v152, 1.0, v152
	v_log_f32_e32 v134, v134
	v_log_f32_e32 v140, v140
	v_log_f32_e32 v146, v146
	v_log_f32_e32 v152, v152
	v_fmac_f32_e32 v135, 0xbf317218, v134
	v_fmac_f32_e32 v141, 0xbf317218, v140
	v_fmac_f32_e32 v147, 0xbf317218, v146
	v_fmac_f32_e32 v153, 0xbf317218, v152
	v_mul_f32_e32 v137, 0x3d800000, v135
	v_mul_f32_e32 v143, 0x3d800000, v141
	v_mul_f32_e32 v149, 0x3d800000, v147
	v_mul_f32_e32 v155, 0x3d800000, v153
	global_store_dword v[10:11], v137, off
	global_store_dword v[10:11], v143, off offset:256
	global_store_dword v[10:11], v149, off offset:512
	global_store_dword v[10:11], v155, off offset:768
	v_lshl_add_u64 v[10:11], v[10:11], 0, s[10:11]
	s_add_i32 s12, s12, 2
	s_cmp_lt_u32 s12, 16
	s_cbranch_scc1 .Lla_rows
	s_waitcnt lgkmcnt(0)
	s_add_i32 s8, s8, 4
	s_mov_b64 s[10:11], 0x400
	v_lshl_add_u64 v[4:5], v[4:5], 0, s[10:11]
	s_cmp_lt_u32 s8, s101
	s_cbranch_scc1 .LBB0_244
	s_waitcnt lgkmcnt(0)
